# baseline (speedup 1.0000x reference)
.LBB0_394:
	s_mov_b64 s[16:17], -1
	s_mov_b64 s[4:5], 0
	s_cmp_lt_i32 s90, 3
	s_mov_b64 s[34:35], 0
	s_cbranch_scc1 .LBB0_445
	s_cmp_gt_i32 s90, 4
	s_cbranch_scc0 .LBB0_435
	s_cmp_gt_i32 s90, 5
	s_cbranch_scc0 .LBB0_400
	s_cmp_eq_u32 s90, 6
	s_mov_b64 s[34:35], -1
	s_cbranch_scc0 .LBB0_399
	v_mov_b32_e32 v248, 0x3b808081
	v_mov_b32_e32 v147, v195
	v_mov_b32_e32 v148, v193
	v_mov_b32_e32 v149, v194
	v_mov_b32_e32 v144, v165
	v_mul_f32_e32 v152, 0xbfb8aa3b, v123
	v_lshlrev_b32_e32 v145, 6, v147
	v_lshlrev_b32_e32 v150, 2, v147
	v_lshlrev_b32_e32 v147, 15, v149
	v_lshlrev_b32_e32 v146, 4, v148
	v_lshl_add_u32 v147, v148, 2, v147
	v_lshlrev_b32_e32 v148, 8, v144
	v_add3_u32 v151, v147, v148, s89
	v_mul_f32_e32 v147, 0xbfb8aa3b, v124
	v_mul_f32_e32 v148, 0xbfb8aa3b, v125
	v_exp_f32_e32 v147, v147
	v_exp_f32_e32 v148, v148
	v_lshl_add_u32 v145, v149, 8, v145
	v_mul_f32_e32 v149, 0xbfb8aa3b, v127
	v_fma_f32 v147, v147, v248, v248
	v_fma_f32 v148, v148, v248, v248
	v_rcp_f32_e32 v147, v147
	v_rcp_f32_e32 v148, v148
	v_exp_f32_e32 v149, v149
	v_exp_f32_e32 v152, v152
	v_cvt_rpi_i32_f32_e32 v147, v147
	v_cvt_rpi_i32_f32_e32 v148, v148
	v_fma_f32 v149, v149, v248, v248
	v_rcp_f32_e32 v149, v149
	v_lshl_or_b32 v147, v148, 8, v147
	v_mul_f32_e32 v148, 0xbfb8aa3b, v126
	v_exp_f32_e32 v148, v148
	v_cvt_rpi_i32_f32_e32 v149, v149
	v_fma_f32 v148, v148, v248, v248
	v_rcp_f32_e32 v148, v148
	v_fma_f32 v152, v152, v248, v248
	v_min_u32_sdwa v149, v149, s81 dst_sel:BYTE_3 dst_unused:UNUSED_PAD src0_sel:DWORD src1_sel:DWORD
	v_rcp_f32_e32 v152, v152
	v_cvt_rpi_i32_f32_e32 v148, v148
	v_cvt_rpi_i32_f32_e32 v152, v152
	v_min_u32_sdwa v148, v148, s81 dst_sel:WORD_1 dst_unused:UNUSED_PAD src0_sel:DWORD src1_sel:DWORD
	v_mul_f32_e32 v153, 0xbfb8aa3b, v119
	v_or3_b32 v148, v147, v148, v149
	v_xor_b32_e32 v147, v150, v144
	v_lshl_add_u32 v147, v147, 4, v151
	ds_write_b32 v147, v148
	v_mul_f32_e32 v148, 0xbfb8aa3b, v120
	v_mul_f32_e32 v149, 0xbfb8aa3b, v121
	v_exp_f32_e32 v148, v148
	v_exp_f32_e32 v149, v149
	v_min_u32_sdwa v152, v152, s81 dst_sel:BYTE_3 dst_unused:UNUSED_PAD src0_sel:DWORD src1_sel:DWORD
	v_exp_f32_e32 v153, v153
	v_fma_f32 v148, v148, v248, v248
	v_fma_f32 v149, v149, v248, v248
	v_rcp_f32_e32 v148, v148
	v_rcp_f32_e32 v149, v149
	v_fma_f32 v153, v153, v248, v248
	v_rcp_f32_e32 v153, v153
	v_cvt_rpi_i32_f32_e32 v148, v148
	v_cvt_rpi_i32_f32_e32 v149, v149
	v_lshl_or_b32 v148, v149, 8, v148
	v_mul_f32_e32 v149, 0xbfb8aa3b, v122
	v_exp_f32_e32 v149, v149
	v_cvt_rpi_i32_f32_e32 v153, v153
	v_mul_f32_e32 v154, 0xbfb8aa3b, v115
	v_exp_f32_e32 v154, v154
	v_fma_f32 v149, v149, v248, v248
	v_rcp_f32_e32 v149, v149
	v_min_u32_sdwa v153, v153, s81 dst_sel:BYTE_3 dst_unused:UNUSED_PAD src0_sel:DWORD src1_sel:DWORD
	v_fma_f32 v154, v154, v248, v248
	v_rcp_f32_e32 v154, v154
	v_cvt_rpi_i32_f32_e32 v149, v149
	v_cvt_rpi_i32_f32_e32 v154, v154
	v_min_u32_sdwa v149, v149, s81 dst_sel:WORD_1 dst_unused:UNUSED_PAD src0_sel:DWORD src1_sel:DWORD
	v_or3_b32 v145, v146, v145, v144
	v_or3_b32 v149, v148, v149, v152
	v_bitop3_b32 v148, v150, v144, 1 bitop3:0x36
	v_lshl_add_u32 v148, v148, 4, v151
	ds_write_b32 v148, v149
	v_mul_f32_e32 v149, 0xbfb8aa3b, v116
	v_mul_f32_e32 v152, 0xbfb8aa3b, v117
	v_exp_f32_e32 v149, v149
	v_exp_f32_e32 v152, v152
	v_min_u32_sdwa v154, v154, s81 dst_sel:BYTE_3 dst_unused:UNUSED_PAD src0_sel:DWORD src1_sel:DWORD
	v_lshlrev_b32_e32 v146, 4, v144
	v_fma_f32 v149, v149, v248, v248
	v_fma_f32 v152, v152, v248, v248
	v_rcp_f32_e32 v149, v149
	v_rcp_f32_e32 v152, v152
	s_and_b32 s17, s13, 0xffff
	s_mov_b32 s16, s12
	v_cvt_rpi_i32_f32_e32 v149, v149
	v_cvt_rpi_i32_f32_e32 v152, v152
	s_mov_b32 s18, s10
	s_mov_b32 s19, s11
	v_lshl_or_b32 v149, v152, 8, v149
	v_mul_f32_e32 v152, 0xbfb8aa3b, v118
	v_exp_f32_e32 v152, v152
	s_nop 0
	v_fma_f32 v152, v152, v248, v248
	v_rcp_f32_e32 v152, v152
	s_nop 0
	v_cvt_rpi_i32_f32_e32 v152, v152
	v_min_u32_sdwa v152, v152, s81 dst_sel:WORD_1 dst_unused:UNUSED_PAD src0_sel:DWORD src1_sel:DWORD
	s_nop 0
	v_or3_b32 v152, v149, v152, v153
	v_bitop3_b32 v149, v150, v144, 2 bitop3:0x36
	v_lshl_add_u32 v149, v149, 4, v151
	ds_write_b32 v149, v152
	v_mul_f32_e32 v152, 0xbfb8aa3b, v112
	v_mul_f32_e32 v153, 0xbfb8aa3b, v113
	v_exp_f32_e32 v152, v152
	v_exp_f32_e32 v153, v153
	v_bitop3_b32 v150, v150, v144, 3 bitop3:0x36
	v_lshl_add_u32 v150, v150, 4, v151
	v_fma_f32 v152, v152, v248, v248
	v_fma_f32 v153, v153, v248, v248
	v_rcp_f32_e32 v152, v152
	v_rcp_f32_e32 v153, v153
	v_mul_f32_e32 v151, 0xbfb8aa3b, v108
	v_exp_f32_e32 v151, v151
	v_cvt_rpi_i32_f32_e32 v152, v152
	v_cvt_rpi_i32_f32_e32 v153, v153
	v_fma_f32 v151, v151, v248, v248
	v_rcp_f32_e32 v151, v151
	v_lshl_or_b32 v152, v153, 8, v152
	v_mul_f32_e32 v153, 0xbfb8aa3b, v114
	v_exp_f32_e32 v153, v153
	v_cvt_rpi_i32_f32_e32 v151, v151
	v_fma_f32 v153, v153, v248, v248
	v_rcp_f32_e32 v153, v153
	s_nop 0
	v_cvt_rpi_i32_f32_e32 v153, v153
	v_min_u32_sdwa v153, v153, s81 dst_sel:WORD_1 dst_unused:UNUSED_PAD src0_sel:DWORD src1_sel:DWORD
	s_nop 0
	v_or3_b32 v152, v152, v153, v154
	ds_write_b32 v150, v152
	v_mul_f32_e32 v152, 0xbfb8aa3b, v109
	v_exp_f32_e32 v152, v152
	v_mul_f32_e32 v153, 0xbfb8aa3b, v111
	v_exp_f32_e32 v153, v153
	v_fma_f32 v152, v152, v248, v248
	v_rcp_f32_e32 v152, v152
	v_fma_f32 v153, v153, v248, v248
	v_rcp_f32_e32 v153, v153
	v_cvt_rpi_i32_f32_e32 v152, v152
	v_cvt_rpi_i32_f32_e32 v153, v153
	v_lshl_or_b32 v151, v152, 8, v151
	v_mul_f32_e32 v152, 0xbfb8aa3b, v110
	v_exp_f32_e32 v152, v152
	v_min_u32_sdwa v153, v153, s81 dst_sel:BYTE_3 dst_unused:UNUSED_PAD src0_sel:DWORD src1_sel:DWORD
	v_fma_f32 v152, v152, v248, v248
	v_rcp_f32_e32 v152, v152
	s_nop 0
	v_cvt_rpi_i32_f32_e32 v152, v152
	v_min_u32_sdwa v152, v152, s81 dst_sel:WORD_1 dst_unused:UNUSED_PAD src0_sel:DWORD src1_sel:DWORD
	s_nop 0
	v_or3_b32 v151, v151, v152, v153
	ds_write_b32 v147, v151 offset:4096
	v_mul_f32_e32 v151, 0xbfb8aa3b, v104
	v_mul_f32_e32 v152, 0xbfb8aa3b, v105
	v_exp_f32_e32 v151, v151
	v_exp_f32_e32 v152, v152
	v_mul_f32_e32 v153, 0xbfb8aa3b, v107
	v_exp_f32_e32 v153, v153
	v_fma_f32 v151, v151, v248, v248
	v_fma_f32 v152, v152, v248, v248
	v_rcp_f32_e32 v151, v151
	v_rcp_f32_e32 v152, v152
	v_fma_f32 v153, v153, v248, v248
	v_rcp_f32_e32 v153, v153
	v_cvt_rpi_i32_f32_e32 v151, v151
	v_cvt_rpi_i32_f32_e32 v152, v152
	v_lshl_or_b32 v151, v152, 8, v151
	v_mul_f32_e32 v152, 0xbfb8aa3b, v106
	v_exp_f32_e32 v152, v152
	v_cvt_rpi_i32_f32_e32 v153, v153
	v_fma_f32 v152, v152, v248, v248
	v_rcp_f32_e32 v152, v152
	v_min_u32_sdwa v153, v153, s81 dst_sel:BYTE_3 dst_unused:UNUSED_PAD src0_sel:DWORD src1_sel:DWORD
	v_cvt_rpi_i32_f32_e32 v152, v152
	v_min_u32_sdwa v152, v152, s81 dst_sel:WORD_1 dst_unused:UNUSED_PAD src0_sel:DWORD src1_sel:DWORD
	s_nop 0
	v_or3_b32 v151, v151, v152, v153
	ds_write_b32 v148, v151 offset:4096
	v_mul_f32_e32 v151, 0xbfb8aa3b, v100
	v_mul_f32_e32 v152, 0xbfb8aa3b, v101
	v_exp_f32_e32 v151, v151
	v_exp_f32_e32 v152, v152
	v_mul_f32_e32 v153, 0xbfb8aa3b, v103
	v_exp_f32_e32 v153, v153
	v_fma_f32 v151, v151, v248, v248
	v_fma_f32 v152, v152, v248, v248
	v_rcp_f32_e32 v151, v151
	v_rcp_f32_e32 v152, v152
	v_fma_f32 v153, v153, v248, v248
	v_rcp_f32_e32 v153, v153
	v_cvt_rpi_i32_f32_e32 v151, v151
	v_cvt_rpi_i32_f32_e32 v152, v152
	v_lshl_or_b32 v151, v152, 8, v151
	v_mul_f32_e32 v152, 0xbfb8aa3b, v102
	v_exp_f32_e32 v152, v152
	v_cvt_rpi_i32_f32_e32 v153, v153
	v_fma_f32 v152, v152, v248, v248
	v_rcp_f32_e32 v152, v152
	v_min_u32_sdwa v153, v153, s81 dst_sel:BYTE_3 dst_unused:UNUSED_PAD src0_sel:DWORD src1_sel:DWORD
	v_cvt_rpi_i32_f32_e32 v152, v152
	v_min_u32_sdwa v152, v152, s81 dst_sel:WORD_1 dst_unused:UNUSED_PAD src0_sel:DWORD src1_sel:DWORD
	s_nop 0
	v_or3_b32 v151, v151, v152, v153
	ds_write_b32 v149, v151 offset:4096
	v_mul_f32_e32 v151, 0xbfb8aa3b, v96
	v_mul_f32_e32 v152, 0xbfb8aa3b, v97
	v_exp_f32_e32 v151, v151
	v_exp_f32_e32 v152, v152
	v_mul_f32_e32 v153, 0xbfb8aa3b, v99
	v_exp_f32_e32 v153, v153
	v_fma_f32 v151, v151, v248, v248
	v_fma_f32 v152, v152, v248, v248
	v_rcp_f32_e32 v151, v151
	v_rcp_f32_e32 v152, v152
	v_fma_f32 v153, v153, v248, v248
	v_rcp_f32_e32 v153, v153
	v_cvt_rpi_i32_f32_e32 v151, v151
	v_cvt_rpi_i32_f32_e32 v152, v152
	v_lshl_or_b32 v151, v152, 8, v151
	v_mul_f32_e32 v152, 0xbfb8aa3b, v98
	v_exp_f32_e32 v152, v152
	v_cvt_rpi_i32_f32_e32 v153, v153
	v_fma_f32 v152, v152, v248, v248
	v_rcp_f32_e32 v152, v152
	v_min_u32_sdwa v153, v153, s81 dst_sel:BYTE_3 dst_unused:UNUSED_PAD src0_sel:DWORD src1_sel:DWORD
	v_cvt_rpi_i32_f32_e32 v152, v152
	v_min_u32_sdwa v152, v152, s81 dst_sel:WORD_1 dst_unused:UNUSED_PAD src0_sel:DWORD src1_sel:DWORD
	s_nop 0
	v_or3_b32 v151, v151, v152, v153
	ds_write_b32 v150, v151 offset:4096
	v_mul_f32_e32 v151, 0xbfb8aa3b, v92
	v_mul_f32_e32 v152, 0xbfb8aa3b, v93
	v_exp_f32_e32 v151, v151
	v_exp_f32_e32 v152, v152
	v_mul_f32_e32 v153, 0xbfb8aa3b, v95
	v_exp_f32_e32 v153, v153
	v_fma_f32 v151, v151, v248, v248
	v_fma_f32 v152, v152, v248, v248
	v_rcp_f32_e32 v151, v151
	v_rcp_f32_e32 v152, v152
	v_fma_f32 v153, v153, v248, v248
	v_rcp_f32_e32 v153, v153
	v_cvt_rpi_i32_f32_e32 v151, v151
	v_cvt_rpi_i32_f32_e32 v152, v152
	v_lshl_or_b32 v151, v152, 8, v151
	v_mul_f32_e32 v152, 0xbfb8aa3b, v94
	v_exp_f32_e32 v152, v152
	v_cvt_rpi_i32_f32_e32 v153, v153
	v_fma_f32 v152, v152, v248, v248
	v_rcp_f32_e32 v152, v152
	v_min_u32_sdwa v153, v153, s81 dst_sel:BYTE_3 dst_unused:UNUSED_PAD src0_sel:DWORD src1_sel:DWORD
	v_cvt_rpi_i32_f32_e32 v152, v152
	v_min_u32_sdwa v152, v152, s81 dst_sel:WORD_1 dst_unused:UNUSED_PAD src0_sel:DWORD src1_sel:DWORD
	s_nop 0
	v_or3_b32 v151, v151, v152, v153
	ds_write_b32 v147, v151 offset:8192
	v_mul_f32_e32 v151, 0xbfb8aa3b, v88
	v_mul_f32_e32 v152, 0xbfb8aa3b, v89
	v_exp_f32_e32 v151, v151
	v_exp_f32_e32 v152, v152
	v_mul_f32_e32 v153, 0xbfb8aa3b, v91
	v_exp_f32_e32 v153, v153
	v_fma_f32 v151, v151, v248, v248
	v_fma_f32 v152, v152, v248, v248
	v_rcp_f32_e32 v151, v151
	v_rcp_f32_e32 v152, v152
	v_fma_f32 v153, v153, v248, v248
	v_rcp_f32_e32 v153, v153
	v_cvt_rpi_i32_f32_e32 v151, v151
	v_cvt_rpi_i32_f32_e32 v152, v152
	v_lshl_or_b32 v151, v152, 8, v151
	v_mul_f32_e32 v152, 0xbfb8aa3b, v90
	v_exp_f32_e32 v152, v152
	v_cvt_rpi_i32_f32_e32 v153, v153
	v_fma_f32 v152, v152, v248, v248
	v_rcp_f32_e32 v152, v152
	v_min_u32_sdwa v153, v153, s81 dst_sel:BYTE_3 dst_unused:UNUSED_PAD src0_sel:DWORD src1_sel:DWORD
	v_cvt_rpi_i32_f32_e32 v152, v152
	v_min_u32_sdwa v152, v152, s81 dst_sel:WORD_1 dst_unused:UNUSED_PAD src0_sel:DWORD src1_sel:DWORD
	s_nop 0
	v_or3_b32 v151, v151, v152, v153
	ds_write_b32 v148, v151 offset:8192
	v_mul_f32_e32 v151, 0xbfb8aa3b, v84
	v_mul_f32_e32 v152, 0xbfb8aa3b, v85
	v_exp_f32_e32 v151, v151
	v_exp_f32_e32 v152, v152
	v_mul_f32_e32 v153, 0xbfb8aa3b, v87
	v_exp_f32_e32 v153, v153
	v_fma_f32 v151, v151, v248, v248
	v_fma_f32 v152, v152, v248, v248
	v_rcp_f32_e32 v151, v151
	v_rcp_f32_e32 v152, v152
	v_fma_f32 v153, v153, v248, v248
	v_rcp_f32_e32 v153, v153
	v_cvt_rpi_i32_f32_e32 v151, v151
	v_cvt_rpi_i32_f32_e32 v152, v152
	v_lshl_or_b32 v151, v152, 8, v151
	v_mul_f32_e32 v152, 0xbfb8aa3b, v86
	v_exp_f32_e32 v152, v152
	v_cvt_rpi_i32_f32_e32 v153, v153
	v_fma_f32 v152, v152, v248, v248
	v_rcp_f32_e32 v152, v152
	v_min_u32_sdwa v153, v153, s81 dst_sel:BYTE_3 dst_unused:UNUSED_PAD src0_sel:DWORD src1_sel:DWORD
	v_cvt_rpi_i32_f32_e32 v152, v152
	v_min_u32_sdwa v152, v152, s81 dst_sel:WORD_1 dst_unused:UNUSED_PAD src0_sel:DWORD src1_sel:DWORD
	s_nop 0
	v_or3_b32 v151, v151, v152, v153
	ds_write_b32 v149, v151 offset:8192
	v_mul_f32_e32 v151, 0xbfb8aa3b, v80
	v_mul_f32_e32 v152, 0xbfb8aa3b, v81
	v_exp_f32_e32 v151, v151
	v_exp_f32_e32 v152, v152
	v_mul_f32_e32 v153, 0xbfb8aa3b, v83
	v_exp_f32_e32 v153, v153
	v_fma_f32 v151, v151, v248, v248
	v_fma_f32 v152, v152, v248, v248
	v_rcp_f32_e32 v151, v151
	v_rcp_f32_e32 v152, v152
	v_fma_f32 v153, v153, v248, v248
	v_rcp_f32_e32 v153, v153
	v_cvt_rpi_i32_f32_e32 v151, v151
	v_cvt_rpi_i32_f32_e32 v152, v152
	v_lshl_or_b32 v151, v152, 8, v151
	v_mul_f32_e32 v152, 0xbfb8aa3b, v82
	v_exp_f32_e32 v152, v152
	v_cvt_rpi_i32_f32_e32 v153, v153
	v_fma_f32 v152, v152, v248, v248
	v_rcp_f32_e32 v152, v152
	v_min_u32_sdwa v153, v153, s81 dst_sel:BYTE_3 dst_unused:UNUSED_PAD src0_sel:DWORD src1_sel:DWORD
	v_cvt_rpi_i32_f32_e32 v152, v152
	v_min_u32_sdwa v152, v152, s81 dst_sel:WORD_1 dst_unused:UNUSED_PAD src0_sel:DWORD src1_sel:DWORD
	s_nop 0
	v_or3_b32 v151, v151, v152, v153
	ds_write_b32 v150, v151 offset:8192
	v_mul_f32_e32 v151, 0xbfb8aa3b, v76
	v_mul_f32_e32 v152, 0xbfb8aa3b, v77
	v_exp_f32_e32 v151, v151
	v_exp_f32_e32 v152, v152
	v_mul_f32_e32 v153, 0xbfb8aa3b, v79
	v_exp_f32_e32 v153, v153
	v_fma_f32 v151, v151, v248, v248
	v_fma_f32 v152, v152, v248, v248
	v_rcp_f32_e32 v151, v151
	v_rcp_f32_e32 v152, v152
	v_fma_f32 v153, v153, v248, v248
	v_rcp_f32_e32 v153, v153
	v_cvt_rpi_i32_f32_e32 v151, v151
	v_cvt_rpi_i32_f32_e32 v152, v152
	v_lshl_or_b32 v151, v152, 8, v151
	v_mul_f32_e32 v152, 0xbfb8aa3b, v78
	v_exp_f32_e32 v152, v152
	v_cvt_rpi_i32_f32_e32 v153, v153
	v_fma_f32 v152, v152, v248, v248
	v_rcp_f32_e32 v152, v152
	v_min_u32_sdwa v153, v153, s81 dst_sel:BYTE_3 dst_unused:UNUSED_PAD src0_sel:DWORD src1_sel:DWORD
	v_cvt_rpi_i32_f32_e32 v152, v152
	v_min_u32_sdwa v152, v152, s81 dst_sel:WORD_1 dst_unused:UNUSED_PAD src0_sel:DWORD src1_sel:DWORD
	s_nop 0
	v_or3_b32 v151, v151, v152, v153
	ds_write_b32 v147, v151 offset:12288
	v_mul_f32_e32 v151, 0xbfb8aa3b, v72
	v_mul_f32_e32 v152, 0xbfb8aa3b, v73
	v_exp_f32_e32 v151, v151
	v_exp_f32_e32 v152, v152
	v_mul_f32_e32 v153, 0xbfb8aa3b, v75
	v_exp_f32_e32 v153, v153
	v_fma_f32 v151, v151, v248, v248
	v_fma_f32 v152, v152, v248, v248
	v_rcp_f32_e32 v151, v151
	v_rcp_f32_e32 v152, v152
	v_fma_f32 v153, v153, v248, v248
	v_rcp_f32_e32 v153, v153
	v_cvt_rpi_i32_f32_e32 v151, v151
	v_cvt_rpi_i32_f32_e32 v152, v152
	v_lshl_or_b32 v151, v152, 8, v151
	v_mul_f32_e32 v152, 0xbfb8aa3b, v74
	v_exp_f32_e32 v152, v152
	v_cvt_rpi_i32_f32_e32 v153, v153
	v_fma_f32 v152, v152, v248, v248
	v_rcp_f32_e32 v152, v152
	v_min_u32_sdwa v153, v153, s81 dst_sel:BYTE_3 dst_unused:UNUSED_PAD src0_sel:DWORD src1_sel:DWORD
	v_cvt_rpi_i32_f32_e32 v152, v152
	v_min_u32_sdwa v152, v152, s81 dst_sel:WORD_1 dst_unused:UNUSED_PAD src0_sel:DWORD src1_sel:DWORD
	s_nop 0
	v_or3_b32 v151, v151, v152, v153
	ds_write_b32 v148, v151 offset:12288
	v_mul_f32_e32 v151, 0xbfb8aa3b, v68
	v_mul_f32_e32 v152, 0xbfb8aa3b, v69
	v_exp_f32_e32 v151, v151
	v_exp_f32_e32 v152, v152
	v_mul_f32_e32 v153, 0xbfb8aa3b, v71
	v_exp_f32_e32 v153, v153
	v_fma_f32 v151, v151, v248, v248
	v_fma_f32 v152, v152, v248, v248
	v_rcp_f32_e32 v151, v151
	v_rcp_f32_e32 v152, v152
	v_fma_f32 v153, v153, v248, v248
	v_rcp_f32_e32 v153, v153
	v_cvt_rpi_i32_f32_e32 v151, v151
	v_cvt_rpi_i32_f32_e32 v152, v152
	v_lshl_or_b32 v151, v152, 8, v151
	v_mul_f32_e32 v152, 0xbfb8aa3b, v70
	v_exp_f32_e32 v152, v152
	v_cvt_rpi_i32_f32_e32 v153, v153
	v_fma_f32 v152, v152, v248, v248
	v_rcp_f32_e32 v152, v152
	v_min_u32_sdwa v153, v153, s81 dst_sel:BYTE_3 dst_unused:UNUSED_PAD src0_sel:DWORD src1_sel:DWORD
	v_cvt_rpi_i32_f32_e32 v152, v152
	v_min_u32_sdwa v152, v152, s81 dst_sel:WORD_1 dst_unused:UNUSED_PAD src0_sel:DWORD src1_sel:DWORD
	s_nop 0
	v_or3_b32 v151, v151, v152, v153
	ds_write_b32 v149, v151 offset:12288
	v_mul_f32_e32 v151, 0xbfb8aa3b, v64
	v_mul_f32_e32 v152, 0xbfb8aa3b, v65
	v_exp_f32_e32 v151, v151
	v_exp_f32_e32 v152, v152
	v_mul_f32_e32 v153, 0xbfb8aa3b, v67
	v_exp_f32_e32 v153, v153
	v_fma_f32 v151, v151, v248, v248
	v_fma_f32 v152, v152, v248, v248
	v_rcp_f32_e32 v151, v151
	v_rcp_f32_e32 v152, v152
	v_fma_f32 v153, v153, v248, v248
	v_rcp_f32_e32 v153, v153
	v_cvt_rpi_i32_f32_e32 v151, v151
	v_cvt_rpi_i32_f32_e32 v152, v152
	v_lshl_or_b32 v151, v152, 8, v151
	v_mul_f32_e32 v152, 0xbfb8aa3b, v66
	v_exp_f32_e32 v152, v152
	v_cvt_rpi_i32_f32_e32 v153, v153
	v_fma_f32 v152, v152, v248, v248
	v_rcp_f32_e32 v152, v152
	v_min_u32_sdwa v153, v153, s81 dst_sel:BYTE_3 dst_unused:UNUSED_PAD src0_sel:DWORD src1_sel:DWORD
	v_cvt_rpi_i32_f32_e32 v152, v152
	v_min_u32_sdwa v152, v152, s81 dst_sel:WORD_1 dst_unused:UNUSED_PAD src0_sel:DWORD src1_sel:DWORD
	s_nop 0
	v_or3_b32 v151, v151, v152, v153
	ds_write_b32 v150, v151 offset:12288
	v_mul_f32_e32 v151, 0xbfb8aa3b, v60
	v_mul_f32_e32 v152, 0xbfb8aa3b, v61
	v_exp_f32_e32 v151, v151
	v_exp_f32_e32 v152, v152
	v_mul_f32_e32 v153, 0xbfb8aa3b, v63
	v_exp_f32_e32 v153, v153
	v_fma_f32 v151, v151, v248, v248
	v_fma_f32 v152, v152, v248, v248
	v_rcp_f32_e32 v151, v151
	v_rcp_f32_e32 v152, v152
	v_fma_f32 v153, v153, v248, v248
	v_rcp_f32_e32 v153, v153
	v_cvt_rpi_i32_f32_e32 v151, v151
	v_cvt_rpi_i32_f32_e32 v152, v152
	v_lshl_or_b32 v151, v152, 8, v151
	v_mul_f32_e32 v152, 0xbfb8aa3b, v62
	v_exp_f32_e32 v152, v152
	v_cvt_rpi_i32_f32_e32 v153, v153
	v_fma_f32 v152, v152, v248, v248
	v_rcp_f32_e32 v152, v152
	v_min_u32_sdwa v153, v153, s81 dst_sel:BYTE_3 dst_unused:UNUSED_PAD src0_sel:DWORD src1_sel:DWORD
	v_cvt_rpi_i32_f32_e32 v152, v152
	v_min_u32_sdwa v152, v152, s81 dst_sel:WORD_1 dst_unused:UNUSED_PAD src0_sel:DWORD src1_sel:DWORD
	s_nop 0
	v_or3_b32 v151, v151, v152, v153
	ds_write_b32 v147, v151 offset:16384
	v_mul_f32_e32 v151, 0xbfb8aa3b, v56
	v_mul_f32_e32 v152, 0xbfb8aa3b, v57
	v_exp_f32_e32 v151, v151
	v_exp_f32_e32 v152, v152
	v_mul_f32_e32 v153, 0xbfb8aa3b, v59
	v_exp_f32_e32 v153, v153
	v_fma_f32 v151, v151, v248, v248
	v_fma_f32 v152, v152, v248, v248
	v_rcp_f32_e32 v151, v151
	v_rcp_f32_e32 v152, v152
	v_fma_f32 v153, v153, v248, v248
	v_rcp_f32_e32 v153, v153
	v_cvt_rpi_i32_f32_e32 v151, v151
	v_cvt_rpi_i32_f32_e32 v152, v152
	v_lshl_or_b32 v151, v152, 8, v151
	v_mul_f32_e32 v152, 0xbfb8aa3b, v58
	v_exp_f32_e32 v152, v152
	v_cvt_rpi_i32_f32_e32 v153, v153
	v_fma_f32 v152, v152, v248, v248
	v_rcp_f32_e32 v152, v152
	v_min_u32_sdwa v153, v153, s81 dst_sel:BYTE_3 dst_unused:UNUSED_PAD src0_sel:DWORD src1_sel:DWORD
	v_cvt_rpi_i32_f32_e32 v152, v152
	v_min_u32_sdwa v152, v152, s81 dst_sel:WORD_1 dst_unused:UNUSED_PAD src0_sel:DWORD src1_sel:DWORD
	s_nop 0
	v_or3_b32 v151, v151, v152, v153
	ds_write_b32 v148, v151 offset:16384
	v_mul_f32_e32 v151, 0xbfb8aa3b, v52
	v_mul_f32_e32 v152, 0xbfb8aa3b, v53
	v_exp_f32_e32 v151, v151
	v_exp_f32_e32 v152, v152
	v_mul_f32_e32 v153, 0xbfb8aa3b, v55
	v_exp_f32_e32 v153, v153
	v_fma_f32 v151, v151, v248, v248
	v_fma_f32 v152, v152, v248, v248
	v_rcp_f32_e32 v151, v151
	v_rcp_f32_e32 v152, v152
	v_fma_f32 v153, v153, v248, v248
	v_rcp_f32_e32 v153, v153
	v_cvt_rpi_i32_f32_e32 v151, v151
	v_cvt_rpi_i32_f32_e32 v152, v152
	v_lshl_or_b32 v151, v152, 8, v151
	v_mul_f32_e32 v152, 0xbfb8aa3b, v54
	v_exp_f32_e32 v152, v152
	v_cvt_rpi_i32_f32_e32 v153, v153
	v_fma_f32 v152, v152, v248, v248
	v_rcp_f32_e32 v152, v152
	v_min_u32_sdwa v153, v153, s81 dst_sel:BYTE_3 dst_unused:UNUSED_PAD src0_sel:DWORD src1_sel:DWORD
	v_cvt_rpi_i32_f32_e32 v152, v152
	v_min_u32_sdwa v152, v152, s81 dst_sel:WORD_1 dst_unused:UNUSED_PAD src0_sel:DWORD src1_sel:DWORD
	s_nop 0
	v_or3_b32 v151, v151, v152, v153
	ds_write_b32 v149, v151 offset:16384
	v_mul_f32_e32 v151, 0xbfb8aa3b, v48
	v_mul_f32_e32 v152, 0xbfb8aa3b, v49
	v_exp_f32_e32 v151, v151
	v_exp_f32_e32 v152, v152
	v_mul_f32_e32 v153, 0xbfb8aa3b, v51
	v_exp_f32_e32 v153, v153
	v_fma_f32 v151, v151, v248, v248
	v_fma_f32 v152, v152, v248, v248
	v_rcp_f32_e32 v151, v151
	v_rcp_f32_e32 v152, v152
	v_fma_f32 v153, v153, v248, v248
	v_rcp_f32_e32 v153, v153
	v_cvt_rpi_i32_f32_e32 v151, v151
	v_cvt_rpi_i32_f32_e32 v152, v152
	v_lshl_or_b32 v151, v152, 8, v151
	v_mul_f32_e32 v152, 0xbfb8aa3b, v50
	v_exp_f32_e32 v152, v152
	v_cvt_rpi_i32_f32_e32 v153, v153
	v_fma_f32 v152, v152, v248, v248
	v_rcp_f32_e32 v152, v152
	v_min_u32_sdwa v153, v153, s81 dst_sel:BYTE_3 dst_unused:UNUSED_PAD src0_sel:DWORD src1_sel:DWORD
	v_cvt_rpi_i32_f32_e32 v152, v152
	v_min_u32_sdwa v152, v152, s81 dst_sel:WORD_1 dst_unused:UNUSED_PAD src0_sel:DWORD src1_sel:DWORD
	s_nop 0
	v_or3_b32 v151, v151, v152, v153
	ds_write_b32 v150, v151 offset:16384
	v_mul_f32_e32 v151, 0xbfb8aa3b, v44
	v_mul_f32_e32 v152, 0xbfb8aa3b, v45
	v_exp_f32_e32 v151, v151
	v_exp_f32_e32 v152, v152
	v_mul_f32_e32 v153, 0xbfb8aa3b, v47
	v_exp_f32_e32 v153, v153
	v_fma_f32 v151, v151, v248, v248
	v_fma_f32 v152, v152, v248, v248
	v_rcp_f32_e32 v151, v151
	v_rcp_f32_e32 v152, v152
	v_fma_f32 v153, v153, v248, v248
	v_rcp_f32_e32 v153, v153
	v_cvt_rpi_i32_f32_e32 v151, v151
	v_cvt_rpi_i32_f32_e32 v152, v152
	v_lshl_or_b32 v151, v152, 8, v151
	v_mul_f32_e32 v152, 0xbfb8aa3b, v46
	v_exp_f32_e32 v152, v152
	v_cvt_rpi_i32_f32_e32 v153, v153
	v_fma_f32 v152, v152, v248, v248
	v_rcp_f32_e32 v152, v152
	v_min_u32_sdwa v153, v153, s81 dst_sel:BYTE_3 dst_unused:UNUSED_PAD src0_sel:DWORD src1_sel:DWORD
	v_cvt_rpi_i32_f32_e32 v152, v152
	v_min_u32_sdwa v152, v152, s81 dst_sel:WORD_1 dst_unused:UNUSED_PAD src0_sel:DWORD src1_sel:DWORD
	s_nop 0
	v_or3_b32 v151, v151, v152, v153
	ds_write_b32 v147, v151 offset:20480
	v_mul_f32_e32 v151, 0xbfb8aa3b, v40
	v_mul_f32_e32 v152, 0xbfb8aa3b, v41
	v_exp_f32_e32 v151, v151
	v_exp_f32_e32 v152, v152
	v_mul_f32_e32 v153, 0xbfb8aa3b, v43
	v_exp_f32_e32 v153, v153
	v_fma_f32 v151, v151, v248, v248
	v_fma_f32 v152, v152, v248, v248
	v_rcp_f32_e32 v151, v151
	v_rcp_f32_e32 v152, v152
	v_fma_f32 v153, v153, v248, v248
	v_rcp_f32_e32 v153, v153
	v_cvt_rpi_i32_f32_e32 v151, v151
	v_cvt_rpi_i32_f32_e32 v152, v152
	v_lshl_or_b32 v151, v152, 8, v151
	v_mul_f32_e32 v152, 0xbfb8aa3b, v42
	v_exp_f32_e32 v152, v152
	v_cvt_rpi_i32_f32_e32 v153, v153
	v_fma_f32 v152, v152, v248, v248
	v_rcp_f32_e32 v152, v152
	v_min_u32_sdwa v153, v153, s81 dst_sel:BYTE_3 dst_unused:UNUSED_PAD src0_sel:DWORD src1_sel:DWORD
	v_cvt_rpi_i32_f32_e32 v152, v152
	v_min_u32_sdwa v152, v152, s81 dst_sel:WORD_1 dst_unused:UNUSED_PAD src0_sel:DWORD src1_sel:DWORD
	s_nop 0
	v_or3_b32 v151, v151, v152, v153
	ds_write_b32 v148, v151 offset:20480
	v_mul_f32_e32 v151, 0xbfb8aa3b, v36
	v_mul_f32_e32 v152, 0xbfb8aa3b, v37
	v_exp_f32_e32 v151, v151
	v_exp_f32_e32 v152, v152
	v_mul_f32_e32 v153, 0xbfb8aa3b, v39
	v_exp_f32_e32 v153, v153
	v_fma_f32 v151, v151, v248, v248
	v_fma_f32 v152, v152, v248, v248
	v_rcp_f32_e32 v151, v151
	v_rcp_f32_e32 v152, v152
	v_fma_f32 v153, v153, v248, v248
	v_rcp_f32_e32 v153, v153
	v_cvt_rpi_i32_f32_e32 v151, v151
	v_cvt_rpi_i32_f32_e32 v152, v152
	v_lshl_or_b32 v151, v152, 8, v151
	v_mul_f32_e32 v152, 0xbfb8aa3b, v38
	v_exp_f32_e32 v152, v152
	v_cvt_rpi_i32_f32_e32 v153, v153
	v_fma_f32 v152, v152, v248, v248
	v_rcp_f32_e32 v152, v152
	v_min_u32_sdwa v153, v153, s81 dst_sel:BYTE_3 dst_unused:UNUSED_PAD src0_sel:DWORD src1_sel:DWORD
	v_cvt_rpi_i32_f32_e32 v152, v152
	v_min_u32_sdwa v152, v152, s81 dst_sel:WORD_1 dst_unused:UNUSED_PAD src0_sel:DWORD src1_sel:DWORD
	s_nop 0
	v_or3_b32 v151, v151, v152, v153
	ds_write_b32 v149, v151 offset:20480
	v_mul_f32_e32 v151, 0xbfb8aa3b, v32
	v_mul_f32_e32 v152, 0xbfb8aa3b, v33
	v_exp_f32_e32 v151, v151
	v_exp_f32_e32 v152, v152
	v_mul_f32_e32 v153, 0xbfb8aa3b, v35
	v_exp_f32_e32 v153, v153
	v_fma_f32 v151, v151, v248, v248
	v_fma_f32 v152, v152, v248, v248
	v_rcp_f32_e32 v151, v151
	v_rcp_f32_e32 v152, v152
	v_fma_f32 v153, v153, v248, v248
	v_rcp_f32_e32 v153, v153
	v_cvt_rpi_i32_f32_e32 v151, v151
	v_cvt_rpi_i32_f32_e32 v152, v152
	v_lshl_or_b32 v151, v152, 8, v151
	v_mul_f32_e32 v152, 0xbfb8aa3b, v34
	v_exp_f32_e32 v152, v152
	v_cvt_rpi_i32_f32_e32 v153, v153
	v_fma_f32 v152, v152, v248, v248
	v_rcp_f32_e32 v152, v152
	v_min_u32_sdwa v153, v153, s81 dst_sel:BYTE_3 dst_unused:UNUSED_PAD src0_sel:DWORD src1_sel:DWORD
	v_cvt_rpi_i32_f32_e32 v152, v152
	v_min_u32_sdwa v152, v152, s81 dst_sel:WORD_1 dst_unused:UNUSED_PAD src0_sel:DWORD src1_sel:DWORD
	s_nop 0
	v_or3_b32 v151, v151, v152, v153
	ds_write_b32 v150, v151 offset:20480
	v_mul_f32_e32 v151, 0xbfb8aa3b, v28
	v_mul_f32_e32 v152, 0xbfb8aa3b, v29
	v_exp_f32_e32 v151, v151
	v_exp_f32_e32 v152, v152
	v_mul_f32_e32 v153, 0xbfb8aa3b, v31
	v_exp_f32_e32 v153, v153
	v_fma_f32 v151, v151, v248, v248
	v_fma_f32 v152, v152, v248, v248
	v_rcp_f32_e32 v151, v151
	v_rcp_f32_e32 v152, v152
	v_fma_f32 v153, v153, v248, v248
	v_rcp_f32_e32 v153, v153
	v_cvt_rpi_i32_f32_e32 v151, v151
	v_cvt_rpi_i32_f32_e32 v152, v152
	v_lshl_or_b32 v151, v152, 8, v151
	v_mul_f32_e32 v152, 0xbfb8aa3b, v30
	v_exp_f32_e32 v152, v152
	v_cvt_rpi_i32_f32_e32 v153, v153
	v_fma_f32 v152, v152, v248, v248
	v_rcp_f32_e32 v152, v152
	v_min_u32_sdwa v153, v153, s81 dst_sel:BYTE_3 dst_unused:UNUSED_PAD src0_sel:DWORD src1_sel:DWORD
	v_cvt_rpi_i32_f32_e32 v152, v152
	v_min_u32_sdwa v152, v152, s81 dst_sel:WORD_1 dst_unused:UNUSED_PAD src0_sel:DWORD src1_sel:DWORD
	s_nop 0
	v_or3_b32 v151, v151, v152, v153
	ds_write_b32 v147, v151 offset:24576
	v_mul_f32_e32 v151, 0xbfb8aa3b, v24
	v_mul_f32_e32 v152, 0xbfb8aa3b, v25
	v_exp_f32_e32 v151, v151
	v_exp_f32_e32 v152, v152
	v_mul_f32_e32 v153, 0xbfb8aa3b, v27
	v_exp_f32_e32 v153, v153
	v_fma_f32 v151, v151, v248, v248
	v_fma_f32 v152, v152, v248, v248
	v_rcp_f32_e32 v151, v151
	v_rcp_f32_e32 v152, v152
	v_fma_f32 v153, v153, v248, v248
	v_rcp_f32_e32 v153, v153
	v_cvt_rpi_i32_f32_e32 v151, v151
	v_cvt_rpi_i32_f32_e32 v152, v152
	v_lshl_or_b32 v151, v152, 8, v151
	v_mul_f32_e32 v152, 0xbfb8aa3b, v26
	v_exp_f32_e32 v152, v152
	v_cvt_rpi_i32_f32_e32 v153, v153
	v_fma_f32 v152, v152, v248, v248
	v_rcp_f32_e32 v152, v152
	v_min_u32_sdwa v153, v153, s81 dst_sel:BYTE_3 dst_unused:UNUSED_PAD src0_sel:DWORD src1_sel:DWORD
	v_cvt_rpi_i32_f32_e32 v152, v152
	v_min_u32_sdwa v152, v152, s81 dst_sel:WORD_1 dst_unused:UNUSED_PAD src0_sel:DWORD src1_sel:DWORD
	s_nop 0
	v_or3_b32 v151, v151, v152, v153
	ds_write_b32 v148, v151 offset:24576
	v_mul_f32_e32 v151, 0xbfb8aa3b, v20
	v_mul_f32_e32 v152, 0xbfb8aa3b, v21
	v_exp_f32_e32 v151, v151
	v_exp_f32_e32 v152, v152
	v_mul_f32_e32 v153, 0xbfb8aa3b, v23
	v_exp_f32_e32 v153, v153
	v_fma_f32 v151, v151, v248, v248
	v_fma_f32 v152, v152, v248, v248
	v_rcp_f32_e32 v151, v151
	v_rcp_f32_e32 v152, v152
	v_fma_f32 v153, v153, v248, v248
	v_rcp_f32_e32 v153, v153
	v_cvt_rpi_i32_f32_e32 v151, v151
	v_cvt_rpi_i32_f32_e32 v152, v152
	v_lshl_or_b32 v151, v152, 8, v151
	v_mul_f32_e32 v152, 0xbfb8aa3b, v22
	v_exp_f32_e32 v152, v152
	v_cvt_rpi_i32_f32_e32 v153, v153
	v_fma_f32 v152, v152, v248, v248
	v_rcp_f32_e32 v152, v152
	v_min_u32_sdwa v153, v153, s81 dst_sel:BYTE_3 dst_unused:UNUSED_PAD src0_sel:DWORD src1_sel:DWORD
	v_cvt_rpi_i32_f32_e32 v152, v152
	v_min_u32_sdwa v152, v152, s81 dst_sel:WORD_1 dst_unused:UNUSED_PAD src0_sel:DWORD src1_sel:DWORD
	s_nop 0
	v_or3_b32 v151, v151, v152, v153
	ds_write_b32 v149, v151 offset:24576
	v_mul_f32_e32 v151, 0xbfb8aa3b, v16
	v_mul_f32_e32 v152, 0xbfb8aa3b, v17
	v_exp_f32_e32 v151, v151
	v_exp_f32_e32 v152, v152
	v_mul_f32_e32 v153, 0xbfb8aa3b, v19
	v_exp_f32_e32 v153, v153
	v_fma_f32 v151, v151, v248, v248
	v_fma_f32 v152, v152, v248, v248
	v_rcp_f32_e32 v151, v151
	v_rcp_f32_e32 v152, v152
	v_fma_f32 v153, v153, v248, v248
	v_rcp_f32_e32 v153, v153
	v_cvt_rpi_i32_f32_e32 v151, v151
	v_cvt_rpi_i32_f32_e32 v152, v152
	v_lshl_or_b32 v151, v152, 8, v151
	v_mul_f32_e32 v152, 0xbfb8aa3b, v18
	v_exp_f32_e32 v152, v152
	v_cvt_rpi_i32_f32_e32 v153, v153
	v_fma_f32 v152, v152, v248, v248
	v_rcp_f32_e32 v152, v152
	v_min_u32_sdwa v153, v153, s81 dst_sel:BYTE_3 dst_unused:UNUSED_PAD src0_sel:DWORD src1_sel:DWORD
	v_cvt_rpi_i32_f32_e32 v152, v152
	v_min_u32_sdwa v152, v152, s81 dst_sel:WORD_1 dst_unused:UNUSED_PAD src0_sel:DWORD src1_sel:DWORD
	s_nop 0
	v_or3_b32 v151, v151, v152, v153
	ds_write_b32 v150, v151 offset:24576
	v_mul_f32_e32 v151, 0xbfb8aa3b, v12
	v_mul_f32_e32 v152, 0xbfb8aa3b, v13
	v_exp_f32_e32 v151, v151
	v_exp_f32_e32 v152, v152
	v_mul_f32_e32 v153, 0xbfb8aa3b, v15
	v_exp_f32_e32 v153, v153
	v_fma_f32 v151, v151, v248, v248
	v_fma_f32 v152, v152, v248, v248
	v_rcp_f32_e32 v151, v151
	v_rcp_f32_e32 v152, v152
	v_fma_f32 v153, v153, v248, v248
	v_rcp_f32_e32 v153, v153
	v_cvt_rpi_i32_f32_e32 v151, v151
	v_cvt_rpi_i32_f32_e32 v152, v152
	v_lshl_or_b32 v151, v152, 8, v151
	v_mul_f32_e32 v152, 0xbfb8aa3b, v14
	v_exp_f32_e32 v152, v152
	v_cvt_rpi_i32_f32_e32 v153, v153
	v_fma_f32 v152, v152, v248, v248
	v_rcp_f32_e32 v152, v152
	v_min_u32_sdwa v153, v153, s81 dst_sel:BYTE_3 dst_unused:UNUSED_PAD src0_sel:DWORD src1_sel:DWORD
	v_cvt_rpi_i32_f32_e32 v152, v152
	v_min_u32_sdwa v152, v152, s81 dst_sel:WORD_1 dst_unused:UNUSED_PAD src0_sel:DWORD src1_sel:DWORD
	s_nop 0
	v_or3_b32 v151, v151, v152, v153
	ds_write_b32 v147, v151 offset:28672
	v_mul_f32_e32 v147, 0xbfb8aa3b, v8
	v_mul_f32_e32 v151, 0xbfb8aa3b, v9
	v_exp_f32_e32 v147, v147
	v_exp_f32_e32 v151, v151
	v_mul_f32_e32 v152, 0xbfb8aa3b, v11
	v_exp_f32_e32 v152, v152
	v_fma_f32 v147, v147, v248, v248
	v_fma_f32 v151, v151, v248, v248
	v_rcp_f32_e32 v147, v147
	v_rcp_f32_e32 v151, v151
	v_fma_f32 v152, v152, v248, v248
	v_rcp_f32_e32 v152, v152
	v_cvt_rpi_i32_f32_e32 v147, v147
	v_cvt_rpi_i32_f32_e32 v151, v151
	v_lshl_or_b32 v147, v151, 8, v147
	v_mul_f32_e32 v151, 0xbfb8aa3b, v10
	v_exp_f32_e32 v151, v151
	v_cvt_rpi_i32_f32_e32 v152, v152
	v_fma_f32 v151, v151, v248, v248
	v_rcp_f32_e32 v151, v151
	v_min_u32_sdwa v152, v152, s81 dst_sel:BYTE_3 dst_unused:UNUSED_PAD src0_sel:DWORD src1_sel:DWORD
	v_cvt_rpi_i32_f32_e32 v151, v151
	v_min_u32_sdwa v151, v151, s81 dst_sel:WORD_1 dst_unused:UNUSED_PAD src0_sel:DWORD src1_sel:DWORD
	s_nop 0
	v_or3_b32 v147, v147, v151, v152
	ds_write_b32 v148, v147 offset:28672
	v_mul_f32_e32 v147, 0xbfb8aa3b, v4
	v_mul_f32_e32 v148, 0xbfb8aa3b, v5
	v_exp_f32_e32 v147, v147
	v_exp_f32_e32 v148, v148
	v_mul_f32_e32 v151, 0xbfb8aa3b, v7
	v_exp_f32_e32 v151, v151
	v_fma_f32 v147, v147, v248, v248
	v_fma_f32 v148, v148, v248, v248
	v_rcp_f32_e32 v147, v147
	v_rcp_f32_e32 v148, v148
	v_fma_f32 v151, v151, v248, v248
	v_rcp_f32_e32 v151, v151
	v_cvt_rpi_i32_f32_e32 v147, v147
	v_cvt_rpi_i32_f32_e32 v148, v148
	v_lshl_or_b32 v147, v148, 8, v147
	v_mul_f32_e32 v148, 0xbfb8aa3b, v6
	v_exp_f32_e32 v148, v148
	v_cvt_rpi_i32_f32_e32 v151, v151
	v_fma_f32 v148, v148, v248, v248
	v_rcp_f32_e32 v148, v148
	v_min_u32_sdwa v151, v151, s81 dst_sel:BYTE_3 dst_unused:UNUSED_PAD src0_sel:DWORD src1_sel:DWORD
	v_cvt_rpi_i32_f32_e32 v148, v148
	v_min_u32_sdwa v148, v148, s81 dst_sel:WORD_1 dst_unused:UNUSED_PAD src0_sel:DWORD src1_sel:DWORD
	s_nop 0
	v_or3_b32 v147, v147, v148, v151
	ds_write_b32 v149, v147 offset:28672
	v_mul_f32_e32 v147, 0xbfb8aa3b, v0
	v_mul_f32_e32 v148, 0xbfb8aa3b, v1
	v_exp_f32_e32 v147, v147
	v_exp_f32_e32 v148, v148
	v_mul_f32_e32 v149, 0xbfb8aa3b, v3
	v_exp_f32_e32 v149, v149
	v_fma_f32 v147, v147, v248, v248
	v_fma_f32 v148, v148, v248, v248
	v_rcp_f32_e32 v147, v147
	v_rcp_f32_e32 v148, v148
	v_fma_f32 v149, v149, v248, v248
	v_rcp_f32_e32 v149, v149
	v_cvt_rpi_i32_f32_e32 v147, v147
	v_cvt_rpi_i32_f32_e32 v148, v148
	v_lshl_or_b32 v147, v148, 8, v147
	v_mul_f32_e32 v148, 0xbfb8aa3b, v2
	v_exp_f32_e32 v148, v148
	v_cvt_rpi_i32_f32_e32 v149, v149
	v_ashrrev_i32_e32 v151, 4, v145
	v_fma_f32 v148, v148, v248, v248
	v_rcp_f32_e32 v148, v148
	v_min_u32_sdwa v149, v149, s81 dst_sel:BYTE_3 dst_unused:UNUSED_PAD src0_sel:DWORD src1_sel:DWORD
	v_cvt_rpi_i32_f32_e32 v148, v148
	v_min_u32_sdwa v148, v148, s81 dst_sel:WORD_1 dst_unused:UNUSED_PAD src0_sel:DWORD src1_sel:DWORD
	s_nop 0
	v_or3_b32 v147, v147, v148, v149
	ds_write_b32 v150, v147 offset:28672
	v_and_b32_e32 v150, 0xf0, v146
	v_xor_b32_e32 v146, v151, v144
	v_lshlrev_b32_e32 v146, 4, v146
	v_and_b32_e32 v146, 0xf0, v146
	v_lshl_or_b32 v146, v151, 8, v146
	v_add_u32_e32 v146, 0x10000, v146
	s_waitcnt lgkmcnt(0)
	s_barrier
	s_waitcnt vmcnt(0)
	ds_read_b128 v[146:149], v146
	v_mad_u64_u32 v[152:153], s[34:35], v151, s33, v[150:151]
	s_waitcnt lgkmcnt(0)
	buffer_store_dwordx4 v[146:149], v152, s[16:19], 0 offen sc1
	s_nop 1
	v_add_u32_e32 v146, 0x200, v145
	v_ashrrev_i32_e32 v151, 4, v146
	v_xor_b32_e32 v146, v151, v144
	v_lshlrev_b32_e32 v146, 4, v146
	v_and_b32_e32 v146, 0xf0, v146
	v_lshl_or_b32 v146, v151, 8, v146
	v_add_u32_e32 v146, 0x10000, v146
	ds_read_b128 v[146:149], v146
	v_mad_u64_u32 v[152:153], s[34:35], v151, s33, v[150:151]
	s_waitcnt lgkmcnt(0)
	buffer_store_dwordx4 v[146:149], v152, s[16:19], 0 offen sc1
	s_nop 1
	v_add_u32_e32 v146, 0x400, v145
	v_ashrrev_i32_e32 v151, 4, v146
	v_xor_b32_e32 v146, v151, v144
	v_lshlrev_b32_e32 v146, 4, v146
	v_and_b32_e32 v146, 0xf0, v146
	v_lshl_or_b32 v146, v151, 8, v146
	v_add_u32_e32 v146, 0x10000, v146
	ds_read_b128 v[146:149], v146
	v_mad_u64_u32 v[152:153], s[34:35], v151, s33, v[150:151]
	s_waitcnt lgkmcnt(0)
	buffer_store_dwordx4 v[146:149], v152, s[16:19], 0 offen sc1
	s_nop 1
	v_add_u32_e32 v146, 0x600, v145
	v_ashrrev_i32_e32 v151, 4, v146
	v_xor_b32_e32 v146, v151, v144
	v_lshlrev_b32_e32 v146, 4, v146
	v_and_b32_e32 v146, 0xf0, v146
	v_lshl_or_b32 v146, v151, 8, v146
	v_add_u32_e32 v146, 0x10000, v146
	ds_read_b128 v[146:149], v146
	v_mad_u64_u32 v[152:153], s[34:35], v151, s33, v[150:151]
	s_waitcnt lgkmcnt(0)
	buffer_store_dwordx4 v[146:149], v152, s[16:19], 0 offen sc1
	s_nop 1
	v_add_u32_e32 v146, 0x800, v145
	v_ashrrev_i32_e32 v151, 4, v146
	v_xor_b32_e32 v146, v151, v144
	v_lshlrev_b32_e32 v146, 4, v146
	v_and_b32_e32 v146, 0xf0, v146
	v_lshl_or_b32 v146, v151, 8, v146
	v_add_u32_e32 v146, 0x10000, v146
	ds_read_b128 v[146:149], v146
	v_mad_u64_u32 v[152:153], s[34:35], v151, s33, v[150:151]
	s_waitcnt lgkmcnt(0)
	buffer_store_dwordx4 v[146:149], v152, s[16:19], 0 offen sc1
	s_nop 1
	v_add_u32_e32 v146, 0xa00, v145
	v_ashrrev_i32_e32 v151, 4, v146
	v_xor_b32_e32 v146, v151, v144
	v_lshlrev_b32_e32 v146, 4, v146
	v_and_b32_e32 v146, 0xf0, v146
	v_lshl_or_b32 v146, v151, 8, v146
	v_add_u32_e32 v146, 0x10000, v146
	ds_read_b128 v[146:149], v146
	v_mad_u64_u32 v[152:153], s[34:35], v151, s33, v[150:151]
	s_waitcnt lgkmcnt(0)
	buffer_store_dwordx4 v[146:149], v152, s[16:19], 0 offen sc1
	s_nop 1
	v_add_u32_e32 v146, 0xc00, v145
	v_ashrrev_i32_e32 v151, 4, v146
	v_xor_b32_e32 v146, v151, v144
	v_lshlrev_b32_e32 v146, 4, v146
	v_and_b32_e32 v146, 0xf0, v146
	v_lshl_or_b32 v146, v151, 8, v146
	v_add_u32_e32 v146, 0x10000, v146
	ds_read_b128 v[146:149], v146
	v_mad_u64_u32 v[152:153], s[34:35], v151, s33, v[150:151]
	v_add_u32_e32 v145, 0xe00, v145
	s_waitcnt lgkmcnt(0)
	buffer_store_dwordx4 v[146:149], v152, s[16:19], 0 offen sc1
	s_nop 1
	v_ashrrev_i32_e32 v148, 4, v145
	v_xor_b32_e32 v144, v148, v144
	v_lshlrev_b32_e32 v144, 4, v144
	v_and_b32_e32 v144, 0xf0, v144
	v_lshl_or_b32 v144, v148, 8, v144
	v_add_u32_e32 v144, 0x10000, v144
	ds_read_b128 v[144:147], v144
	v_mad_u64_u32 v[148:149], s[34:35], v148, s33, v[150:151]
	s_mov_b64 s[34:35], 0
	s_waitcnt lgkmcnt(0)
	buffer_store_dwordx4 v[144:147], v148, s[16:19], 0 offen sc1
	s_waitcnt lgkmcnt(0)
	s_barrier
